# p2_mix: workgroups with bit 3 of their id set run the P2 conv units before the K^T V units (phase mix: half the CUs stream while half compute), on top of v6
# speedup vs baseline: 1.0053x; 1.0009x over previous
; #define LAS __attribute__((address_space(3)))
; template <bool WITHQ> __device__ __forceinline__ void raw_load(UnitRaw& r, int u, const bf16* PROJ, const int* pos, int tid) {
;     const int bh = u >> 6, c = u & 63, b = bh >> 2, h = bh & 3; const size_t row0 = (size_t)b * SEQ + (size_t)c * 128;
; #pragma unroll
;     for (int i = 0; i < 2; ++i) { const int it = tid + 512 * i, dc = it & 7, j = it >> 3; const bf16* qr = PROJ + (row0 + j) * INC + h * 128 + dc * 8; const bf16* kr = qr + 512;
;         if (WITHQ) { r.a1[i] = *(const u32x4*)qr; r.a2[i] = *(const u32x4*)(qr + 64); }
;         r.k1[i] = *(const u32x4*)kr; r.k2[i] = *(const u32x4*)(kr + 64); r.p[i] = (float)pos[row0 + j]; }
; #pragma unroll
;     for (int i = 0; i < 4; ++i) { const int it = tid + 512 * i, ec = it & 15, j = it >> 4; r.v[i] = *(const u32x4*)(PROJ + (row0 + j) * INC + 1024 + h * 128 + ec * 8); }
; }
; __device__ __forceinline__ void stage_vt_regs(LAS bf16* VT, const UnitRaw& r, int tid) {
; #pragma unroll
;     for (int i = 0; i < 4; ++i) { const int it = tid + 512 * i, ec = it & 15, j = it >> 4; const u32x4 w = r.v[i];
;         const int jsw = (((j >> 3) ^ (ec & 7)) << 3) | (j & 7);
; #pragma unroll
;         for (int e = 0; e < 4; ++e) { VT[(ec * 8 + 2 * e) * LDT + jsw] = (bf16)(w[e] & 0xffffu); VT[(ec * 8 + 2 * e + 1) * LDT + jsw] = (bf16)(w[e] >> 16); } }
; }
; __device__ __forceinline__ void stage_vt(LAS bf16* VT, const bf16* PROJ, size_t row0, int h, int tid) {
;     for (int it = tid; it < 2048; it += 512) { const int ec = it & 15, j = it >> 4;
;         const u32x4 w = *(const u32x4*)(PROJ + (row0 + j) * INC + 1024 + h * 128 + ec * 8);
;         const int jsw = (((j >> 3) ^ (ec & 7)) << 3) | (j & 7);
; #pragma unroll
;         for (int e = 0; e < 4; ++e) { VT[(ec * 8 + 2 * e) * LDT + jsw] = (bf16)(w[e] & 0xffffu); VT[(ec * 8 + 2 * e + 1) * LDT + jsw] = (bf16)(w[e] >> 16); } }
; }
; __global__ void __launch_bounds__(512, 2) fwd_mega(Args a) {
;     ...
;         { UnitRaw raw; int u = bid; if (u < 512) raw_load<false>(raw, u, PROJ, pos, tid);
;           for (; u < 512; u += G) kv_unit(lds, u, PROJ, pos, a.in[5], a.in[6], KVC, tid, raw, (u + G < 512) ? u + G : -1); }
;         for (int u = bid; u < 512; u += G) conv_unit(lds, u, PROJ, a.in[9], a.in[10], a.in[11], a.in[12], MIX, tid, wsr);
.LBB0_213:
	s_cmp_lt_i32 s86, 3
	s_cselect_b64 s[4:5], -1, 0
	s_add_u32 s70, s84, 0x4800000
	s_addc_u32 s71, s85, 0
	s_add_u32 s8, s84, 0x6800000
	s_addc_u32 s9, s85, 0
	v_writelane_b32 v255, s8, 26
	s_and_b64 s[0:1], s[4:5], s[0:1]
	s_andn2_b64 vcc, exec, s[0:1]
	v_writelane_b32 v255, s9, 27
	s_cbranch_vccnz .LBB0_225
	s_cmpk_gt_i32 s2, 0x1ff
	s_cbranch_scc1 .LBB0_225
	s_mov_b32 s100, 0
	s_bitcmp1_b32 s2, 3
	s_cbranch_scc0 .Lmix_kv
	s_mov_b32 s100, 1
	v_lshrrev_b32_e32 v75, 6, v128
	v_lshrrev_b32_e32 v32, 4, v128
	v_lshlrev_b32_e32 v76, 3, v128
	v_lshlrev_b32_e32 v86, 11, v75
	s_branch .LBB0_219
.Lmix_kv:
	v_and_b32_e32 v0, 7, v128
	v_lshlrev_b32_e32 v1, 3, v0
	v_cvt_f32_ubyte0_e32 v2, v1
	v_lshrrev_b32_e32 v34, 3, v128
	v_lshrrev_b32_e32 v75, 6, v128
	v_mul_f32_e32 v2, 0xbe549a78, v2
	v_xor_b32_e32 v3, 0x7f, v34
	v_exp_f32_e32 v35, v2
	v_bfe_u32 v2, v128, 3, 3
	v_cvt_f32_ubyte0_e32 v41, v3
	v_bitop3_b32 v3, v75, v128, 7 bitop3:0x78
	v_lshl_or_b32 v3, v3, 3, v2
	s_movk_i32 s4, 0x440
	v_mad_u32_u24 v4, v0, s4, v3
	v_lshl_add_u32 v55, v4, 1, 0
	v_or_b32_e32 v4, 1, v1
	v_cvt_f32_ubyte0_e32 v5, v4
	v_mul_f32_e32 v5, 0xbe549a78, v5
	s_movk_i32 s8, 0x88
	v_exp_f32_e32 v56, v5
	v_mad_u32_u24 v5, v4, s8, v3
	v_lshl_add_u32 v57, v5, 1, 0
	v_or_b32_e32 v5, 2, v1
	v_cvt_f32_ubyte0_e32 v5, v5
	v_mul_f32_e32 v5, 0xbe549a78, v5
	v_exp_f32_e32 v58, v5
	v_mad_u32_u24 v5, v4, s8, s8
	v_add_u32_e32 v6, v5, v3
	v_lshl_add_u32 v59, v6, 1, 0
	v_or_b32_e32 v6, 3, v1
	v_cvt_f32_ubyte0_e32 v6, v6
	v_mul_f32_e32 v6, 0xbe549a78, v6
	v_exp_f32_e32 v60, v6
	v_mov_b32_e32 v6, 0x110
	v_mad_u32_u24 v6, v4, s8, v6
	v_add_u32_e32 v7, v6, v3
	v_lshl_add_u32 v61, v7, 1, 0
	v_or_b32_e32 v7, 4, v1
	v_cvt_f32_ubyte0_e32 v7, v7
	v_mul_f32_e32 v7, 0xbe549a78, v7
	v_exp_f32_e32 v62, v7
	v_mov_b32_e32 v7, 0x198
	v_mad_u32_u24 v7, v4, s8, v7
	v_add_u32_e32 v8, v7, v3
	v_lshl_add_u32 v63, v8, 1, 0
	v_or_b32_e32 v8, 5, v1
	v_cvt_f32_ubyte0_e32 v8, v8
	v_mul_f32_e32 v8, 0xbe549a78, v8
	v_exp_f32_e32 v64, v8
	v_mov_b32_e32 v8, 0x220
	v_mad_u32_u24 v8, v4, s8, v8
	v_add_u32_e32 v9, v8, v3
	v_lshl_add_u32 v65, v9, 1, 0
	v_or_b32_e32 v9, 6, v1
	v_or_b32_e32 v1, 7, v1
	v_cvt_f32_ubyte0_e32 v9, v9
	v_cvt_f32_ubyte0_e32 v1, v1
	v_mul_f32_e32 v9, 0xbe549a78, v9
	v_mul_f32_e32 v1, 0xbe549a78, v1
	v_exp_f32_e32 v66, v9
	v_mov_b32_e32 v9, 0x2a8
	v_exp_f32_e32 v68, v1
	v_mov_b32_e32 v1, 0x330
	v_mad_u32_u24 v9, v4, s8, v9
	v_mad_u32_u24 v1, v4, s8, v1
	v_add_u32_e32 v10, v9, v3
	v_add_u32_e32 v3, v1, v3
	v_lshl_add_u32 v69, v3, 1, 0
	v_add_u32_e32 v3, 0x200, v128
	v_lshrrev_b32_e32 v36, 3, v3
	v_lshl_add_u32 v67, v10, 1, 0
	v_sub_u32_e32 v10, 0x7f, v36
	v_cvt_f32_i32_e32 v70, v10
	v_lshrrev_b32_e32 v10, 6, v3
	v_bitop3_b32 v10, v10, v128, 7 bitop3:0x78
	v_lshl_or_b32 v2, v10, 3, v2
	v_mad_u32_u24 v4, v4, s8, v2
	v_lshl_add_u32 v73, v4, 1, 0
	v_add_u32_e32 v4, v2, v5
	v_lshl_add_u32 v74, v4, 1, 0
	v_add_u32_e32 v4, v2, v6
	v_lshl_add_u32 v77, v4, 1, 0
	v_add_u32_e32 v4, v2, v7
	v_add_u32_e32 v1, v2, v1
	v_mad_u32_u24 v10, v0, s4, v2
	v_lshl_add_u32 v78, v4, 1, 0
	v_add_u32_e32 v4, v2, v8
	v_lshl_add_u32 v81, v1, 1, 0
	v_lshlrev_b32_e32 v76, 3, v128
	v_lshrrev_b32_e32 v1, 7, v128
	s_add_i32 s4, 0, 0x11000
	s_movk_i32 s3, 0x110
	v_lshl_add_u32 v79, v4, 1, 0
	v_add_u32_e32 v4, v2, v9
	v_and_b32_e32 v48, 0x78, v76
	v_mov_b32_e32 v33, s4
	v_and_b32_e32 v5, 14, v34
	v_bitop3_b32 v0, v1, v0, 8 bitop3:0x36
	v_lshl_add_u32 v80, v4, 1, 0
	v_mad_u32_u24 v4, v48, s3, v33
	v_lshl_or_b32 v0, v0, 4, v5
	v_bitop3_b32 v2, v1, v128, 7 bitop3:0x78
	v_add_u32_e32 v84, v4, v0
	v_add_u32_e32 v0, 0x600, v128
	v_lshl_or_b32 v2, v2, 4, v5
	v_lshrrev_b32_e32 v1, 7, v0
	s_ashr_i32 s8, s2, 8
	v_add_u32_e32 v82, v4, v2
	v_lshrrev_b32_e32 v2, 7, v3
	v_bitop3_b32 v1, v1, v128, 7 bitop3:0x78
	s_ashr_i32 s9, s8, 31
	s_lshl_b32 s4, s2, 7
	v_bitop3_b32 v2, v2, v128, 7 bitop3:0x78
	v_lshl_or_b32 v1, v1, 4, v5
	v_mov_b32_e32 v39, 0
	s_lshl_b64 s[8:9], s[8:9], 13
	s_and_b32 s4, s4, 0x1f80
	v_lshl_or_b32 v2, v2, 4, v5
	v_add_u32_e32 v85, v4, v1
	v_lshlrev_b32_e32 v1, 4, v128
	v_lshrrev_b32_e32 v44, 4, v0
	v_mov_b32_e32 v45, v39
	s_or_b32 s8, s8, s4
	v_add_u32_e32 v83, v4, v2
	v_and_b32_e32 v38, 0x70, v1
	v_lshrrev_b32_e32 v40, 4, v3
	v_lshl_add_u64 v[0:1], s[8:9], 0, v[44:45]
	s_movk_i32 s14, 0x1800
	v_mov_b64_e32 v[2:3], s[6:7]
	v_mad_u64_u32 v[4:5], s[10:11], v0, s14, v[2:3]
	s_lshl_b32 s4, s2, 2
	v_lshrrev_b32_e32 v32, 4, v128
	s_mov_b32 s5, 0
	v_mad_i32_i24 v5, v1, s14, v5
	s_and_b32 s4, s4, 0x300
	v_or_b32_e32 v42, 64, v32
	v_lshl_add_u64 v[0:1], v[4:5], 0, s[4:5]
	v_lshlrev_b32_e32 v4, 1, v48
; #define LAS __attribute__((address_space(3)))
; __device__ __forceinline__ unsigned pk2(float lo, float hi) { return pg8::cvt_pk_bf16(lo, hi); }
; #define MFMA16(a, b, c) __builtin_amdgcn_mfma_f32_16x16x32_bf16((a), (b), (c), 0, 0, 0)
; template <bool WITHQ> __device__ __forceinline__ void raw_load(UnitRaw& r, int u, const bf16* PROJ, const int* pos, int tid) {
;     const int bh = u >> 6, c = u & 63, b = bh >> 2, h = bh & 3; const size_t row0 = (size_t)b * SEQ + (size_t)c * 128;
; #pragma unroll
;     for (int i = 0; i < 2; ++i) { const int it = tid + 512 * i, dc = it & 7, j = it >> 3; const bf16* qr = PROJ + (row0 + j) * INC + h * 128 + dc * 8; const bf16* kr = qr + 512;
;         if (WITHQ) { r.a1[i] = *(const u32x4*)qr; r.a2[i] = *(const u32x4*)(qr + 64); }
;         r.k1[i] = *(const u32x4*)kr; r.k2[i] = *(const u32x4*)(kr + 64); r.p[i] = (float)pos[row0 + j]; }
; #pragma unroll
;     for (int i = 0; i < 4; ++i) { const int it = tid + 512 * i, ec = it & 15, j = it >> 4; r.v[i] = *(const u32x4*)(PROJ + (row0 + j) * INC + 1024 + h * 128 + ec * 8); }
; }
; __device__ __forceinline__ void kv_unit(LAS unsigned char* lds, int u, const bf16* PROJ, const int* pos, const float* dec_f, const float* dec_b, bf16* KVc, int tid, UnitRaw& raw, int next_u) {
;     ...
;     f32x4 accf[8], accb[8];
; #pragma unroll
;     for (int n = 0; n < 8; ++n) { accf[n] = (f32x4){0.f, 0.f, 0.f, 0.f}; accb[n] = (f32x4){0.f, 0.f, 0.f, 0.f}; }
; #pragma unroll
;     for (int kk = 0; kk < 4; ++kk) { const bf16x8 xf = *(const LAS bf16x8*)(VT + (wave * 16 + fr) * LDT + (((kk * 4 + fq) ^ ((2 * wave + (fr >> 3)) & 7)) << 3));
; #pragma unroll
;         for (int n = 0; n < 8; ++n) { const int co = (((kk * 4 + fq) ^ ((2 * n + (fr >> 3)) & 7)) << 3); const bf16x8 yf = *(const LAS bf16x8*)(KTf + (n * 16 + fr) * LDT + co); const bf16x8 yb = *(const LAS bf16x8*)(KTb + (n * 16 + fr) * LDT + co);
;             accf[n] = MFMA16(yf, xf, accf[n]); accb[n] = MFMA16(yb, xf, accb[n]); } }
;     bf16* of = KVc + ((size_t)bh * 64 + c) * 16384 + (wave * 16 + fr) * 128 + 4 * fq;
;     bf16* ob = of + (size_t)8 * 64 * 16384;
; #pragma unroll
;     for (int n = 0; n < 8; ++n) { u32x2 w; w.x = pk2(accf[n][0], accf[n][1]); w.y = pk2(accf[n][2], accf[n][3]); *(u32x2*)(of + n * 16) = w;
;         u32x2 v; v.x = pk2(accb[n][0], accb[n][1]); v.y = pk2(accb[n][2], accb[n][3]); *(u32x2*)(ob + n * 16) = v; }
	v_mov_b32_e32 v5, v39
	v_lshl_add_u64 v[28:29], v[0:1], 0, v[4:5]
	v_or_b32_e32 v0, s8, v42
	v_mad_u64_u32 v[0:1], s[10:11], v0, s14, v[2:3]
	v_mov_b32_e32 v87, 0x1800
	v_mad_i32_i24 v1, s9, v87, v1
	v_lshl_add_u64 v[0:1], v[0:1], 0, s[4:5]
	v_lshl_add_u64 v[24:25], v[0:1], 0, v[4:5]
	v_or_b32_e32 v0, s8, v40
	v_mad_u64_u32 v[0:1], s[10:11], v0, s14, v[2:3]
	v_mad_i32_i24 v1, s9, v87, v1
	v_mov_b32_e32 v37, v39
	v_lshl_add_u64 v[0:1], v[0:1], 0, s[4:5]
	v_lshl_add_u64 v[20:21], v[0:1], 0, v[4:5]
	v_lshl_add_u64 v[0:1], s[8:9], 0, v[36:37]
	v_or_b32_e32 v8, s8, v34
	v_mov_b32_e32 v9, s9
	v_lshl_add_u32 v72, v10, 1, 0
	v_lshl_add_u64 v[6:7], v[0:1], 2, s[12:13]
	v_lshl_add_u64 v[10:11], v[8:9], 2, s[12:13]
	global_load_dword v49, v[10:11], off
	global_load_dword v51, v[6:7], off
	v_or_b32_e32 v6, s8, v32
	v_mad_u64_u32 v[2:3], s[10:11], v6, s14, v[2:3]
	v_mad_i32_i24 v3, s9, v87, v3
	s_add_u32 s10, s6, s4
	v_lshl_add_u64 v[2:3], v[2:3], 0, s[4:5]
	s_addc_u32 s11, s7, 0
	v_lshl_add_u64 v[16:17], v[2:3], 0, v[4:5]
	v_lshl_add_u64 v[2:3], s[10:11], 0, v[38:39]
	v_mad_u64_u32 v[12:13], s[10:11], v0, s14, v[2:3]
	v_mad_u64_u32 v[4:5], s[10:11], v8, s14, v[2:3]
	v_mad_i32_i24 v13, v1, s14, v13
	v_mad_i32_i24 v5, s9, v87, v5
	global_load_dwordx4 v[0:3], v[4:5], off offset:1024
	s_nop 0
	global_load_dwordx4 v[4:7], v[4:5], off offset:1152
	s_nop 0
	global_load_dwordx4 v[8:11], v[12:13], off offset:1024
	s_nop 0
	global_load_dwordx4 v[12:15], v[12:13], off offset:1152
	s_nop 0
	global_load_dwordx4 v[16:19], v[16:17], off offset:2048
	s_nop 0
	global_load_dwordx4 v[20:23], v[20:21], off offset:2048
	s_nop 0
	global_load_dwordx4 v[24:27], v[24:25], off offset:2048
	s_nop 0
	global_load_dwordx4 v[28:31], v[28:29], off offset:2048
	v_lshl_add_u64 v[46:47], s[6:7], 0, v[38:39]
	v_and_b32_e32 v38, 15, v128
	v_lshl_or_b32 v52, v75, 4, v38
	v_mad_u32_u24 v52, v52, s3, v33
	v_lshrrev_b32_e32 v33, 5, v128
	v_bfe_u32 v50, v128, 4, 2
	v_bfe_u32 v53, v128, 3, 1
	v_and_b32_e32 v33, 6, v33
	v_bitop3_b32 v54, v33, v50, v53 bitop3:0x36
	v_mul_u32_u24_e32 v86, 0x88, v38
	v_lshlrev_b32_e32 v105, 4, v54
	v_bitop3_b32 v54, v53, v32, 3 bitop3:0x78
	v_lshl_add_u32 v86, v86, 1, 0
	v_lshl_add_u32 v88, v54, 4, v86
	v_bitop3_b32 v54, v53, v50, 2 bitop3:0x36
	v_lshl_add_u32 v89, v54, 4, v86
	v_bitop3_b32 v54, v53, v50, 4 bitop3:0x36
	v_lshl_add_u32 v90, v54, 4, v86
	v_bitop3_b32 v54, v53, v50, 6 bitop3:0x36
	v_lshl_add_u32 v91, v54, 4, v86
	v_or_b32_e32 v54, 4, v50
	v_bitop3_b32 v92, v33, v54, v53 bitop3:0x36
	v_bitop3_b32 v93, v53, v54, 2 bitop3:0x36
	v_bitop3_b32 v54, v53, v54, 6 bitop3:0x36
	v_lshl_add_u32 v95, v54, 4, v86
	v_or_b32_e32 v54, 8, v50
	v_bitop3_b32 v96, v33, v54, v53 bitop3:0x36
	v_bitop3_b32 v97, v53, v54, 2 bitop3:0x36
	v_bitop3_b32 v98, v53, v54, 4 bitop3:0x36
	v_bitop3_b32 v54, v53, v54, 6 bitop3:0x36
	v_lshl_add_u32 v99, v54, 4, v86
	v_or_b32_e32 v54, 12, v50
	v_bitop3_b32 v33, v33, v54, v53 bitop3:0x36
	v_lshlrev_b32_e32 v108, 4, v33
	v_bitop3_b32 v33, v50, v53, 12 bitop3:0x36
	v_lshl_add_u32 v100, v33, 4, v86
	v_bitop3_b32 v33, v53, v54, 2 bitop3:0x36
	v_lshl_add_u32 v101, v33, 4, v86
	v_bitop3_b32 v33, v53, v54, 4 bitop3:0x36
	v_lshl_add_u32 v102, v33, 4, v86
	v_bitop3_b32 v33, v53, v54, 6 bitop3:0x36
	v_lshlrev_b32_e32 v106, 4, v92
	v_bitop3_b32 v92, v50, v53, 4 bitop3:0x36
	v_bitop3_b32 v94, v53, v50, 4 bitop3:0x14
	v_lshlrev_b32_e32 v107, 4, v96
	v_bitop3_b32 v96, v50, v53, 8 bitop3:0x36
	v_lshl_add_u32 v103, v33, 4, v86
	v_lshl_add_u32 v92, v92, 4, v86
	v_lshl_add_u32 v93, v93, 4, v86
	v_lshl_add_u32 v94, v94, 4, v86
	v_lshl_add_u32 v96, v96, 4, v86
	v_lshl_add_u32 v97, v97, 4, v86
	v_lshl_add_u32 v98, v98, 4, v86
	v_lshlrev_b32_e32 v86, 11, v75
	v_lshl_or_b32 v38, v38, 7, v86
	v_lshlrev_b32_e32 v50, 2, v50
	v_readlane_b32 s8, v255, 8
	v_cvt_f32_ubyte0_e32 v43, v34
	v_cvt_f32_ubyte0_e32 v71, v36
	s_lshl_b32 s15, s2, 14
	s_lshl_b32 s24, s8, 14
	s_mov_b32 s25, 0xbfb8aa3b
	s_waitcnt vmcnt(0)
	v_cvt_f32_i32_e32 v54, v49
	v_cvt_f32_i32_e32 v33, v51
	s_mov_b32 s26, 0x42ce8ed0
	s_mov_b32 s27, 0xc2b17218
	s_mov_b32 s28, 0x7f800000
	s_mov_b32 s29, 0x3f2aaaab
	v_mov_b32_e32 v104, 0x3ecc95a3
	s_mov_b32 s30, 0x3f317218
	s_mov_b32 s31, 0x33800000
	v_lshlrev_b32_e32 v48, 1, v48
	v_add_u32_e32 v105, v52, v105
	v_add_u32_e32 v106, v52, v106
	v_add_u32_e32 v107, v52, v107
	v_add_u32_e32 v108, v52, v108
	v_lshlrev_b32_e32 v38, 1, v38
	v_lshlrev_b32_e32 v50, 1, v50
	s_mov_b32 s33, 0x1000000
	v_mov_b32_e32 v109, 0x7f800000
	v_mov_b32_e32 v52, 0x3f317218
	s_mov_b32 s34, s2
	v_readlane_b32 s9, v255, 9
	s_branch .LBB0_217

; __global__ void __launch_bounds__(512, 2) fwd_mega(Args a) {
;     ...
;           for (; u < 512; u += G) kv_unit(lds, u, PROJ, pos, a.in[5], a.in[6], KVC, tid, raw, (u + G < 512) ? u + G : -1); }
;         for (int u = bid; u < 512; u += G) conv_unit(lds, u, PROJ, a.in[9], a.in[10], a.in[11], a.in[12], MIX, tid, wsr);
.Lmix_kvdone:
	s_cmp_eq_u32 s100, 2
	s_cbranch_scc1 .LBB0_225

; __global__ void __launch_bounds__(512, 2) fwd_mega(Args a) {
;     ...
;         for (int u = bid; u < 512; u += G) conv_unit(lds, u, PROJ, a.in[9], a.in[10], a.in[11], a.in[12], MIX, tid, wsr);
.Lmix_cvdone:
	s_cmp_eq_u32 s100, 1
	s_cbranch_scc0 .LBB0_225
	s_mov_b32 s100, 2
	s_branch .Lmix_kv
